# W_C inner loop double-buffered; selection ballot counts de-serialized via distinct SGPR pairs
# speedup vs baseline: 1.2167x; 1.0013x over previous
.LBB0_123:
	v_add_co_u32_e32 v102, vcc, s27, v4
	global_load_dword v0, v[4:5], off
	s_nop 0
	v_addc_co_u32_e32 v103, vcc, 0, v5, vcc
	v_lshl_add_u64 v[106:107], v[6:7], 0, s[24:25]
	v_add_co_u32_e32 v104, vcc, s28, v4
	s_add_u32 s24, s24, 16
	s_nop 0
	v_addc_co_u32_e32 v105, vcc, 0, v5, vcc
	global_load_dwordx4 v[18:21], v[106:107], off
	global_load_dwordx4 v[22:25], v[106:107], off offset:256
	global_load_dwordx4 v[26:29], v[106:107], off offset:512
	global_load_dwordx4 v[30:33], v[106:107], off offset:768
	global_load_dwordx4 v[34:37], v[106:107], off offset:1024
	global_load_dwordx4 v[38:41], v[106:107], off offset:1280
	global_load_dwordx4 v[42:45], v[106:107], off offset:1536
	global_load_dwordx4 v[46:49], v[106:107], off offset:1792
	global_load_dword v56, v[102:103], off offset:-4096
	global_load_dword v58, v[102:103], off
	global_load_dword v60, v[104:105], off
	s_addc_u32 s25, s25, 0
	v_lshl_add_u64 v[4:5], v[4:5], 0, s[16:17]
.Lwc_loop:
	v_add_co_u32_e32 v102, vcc, s27, v4
	global_load_dword v62, v[4:5], off
	s_nop 0
	v_addc_co_u32_e32 v103, vcc, 0, v5, vcc
	v_lshl_add_u64 v[106:107], v[6:7], 0, s[24:25]
	v_add_co_u32_e32 v104, vcc, s28, v4
	s_add_u32 s24, s24, 16
	s_nop 0
	v_addc_co_u32_e32 v105, vcc, 0, v5, vcc
	global_load_dwordx4 v[70:73], v[106:107], off
	global_load_dwordx4 v[74:77], v[106:107], off offset:256
	global_load_dwordx4 v[78:81], v[106:107], off offset:512
	global_load_dwordx4 v[82:85], v[106:107], off offset:768
	global_load_dwordx4 v[86:89], v[106:107], off offset:1024
	global_load_dwordx4 v[90:93], v[106:107], off offset:1280
	global_load_dwordx4 v[94:97], v[106:107], off offset:1536
	global_load_dwordx4 v[98:101], v[106:107], off offset:1792
	global_load_dword v64, v[102:103], off offset:-4096
	global_load_dword v66, v[102:103], off
	global_load_dword v68, v[104:105], off
	s_addc_u32 s25, s25, 0
	v_lshl_add_u64 v[4:5], v[4:5], 0, s[16:17]
	s_waitcnt vmcnt(12)
	v_fmac_f32_e32 v10, v0, v18
	v_fmac_f32_e32 v11, v0, v22
	v_fmac_f32_e32 v12, v0, v26
	v_fmac_f32_e32 v13, v0, v30
	v_fmac_f32_e32 v14, v0, v34
	v_fmac_f32_e32 v15, v0, v38
	v_fmac_f32_e32 v8, v0, v42
	v_fmac_f32_e32 v9, v0, v46
	v_fmac_f32_e32 v10, v56, v19
	v_fmac_f32_e32 v11, v56, v23
	v_fmac_f32_e32 v12, v56, v27
	v_fmac_f32_e32 v13, v56, v31
	v_fmac_f32_e32 v14, v56, v35
	v_fmac_f32_e32 v15, v56, v39
	v_fmac_f32_e32 v8, v56, v43
	v_fmac_f32_e32 v9, v56, v47
	v_fmac_f32_e32 v10, v58, v20
	v_fmac_f32_e32 v11, v58, v24
	v_fmac_f32_e32 v12, v58, v28
	v_fmac_f32_e32 v13, v58, v32
	v_fmac_f32_e32 v14, v58, v36
	v_fmac_f32_e32 v15, v58, v40
	v_fmac_f32_e32 v8, v58, v44
	v_fmac_f32_e32 v9, v58, v48
	v_fmac_f32_e32 v10, v60, v21
	v_fmac_f32_e32 v11, v60, v25
	v_fmac_f32_e32 v12, v60, v29
	v_fmac_f32_e32 v13, v60, v33
	v_fmac_f32_e32 v14, v60, v37
	v_fmac_f32_e32 v15, v60, v41
	v_fmac_f32_e32 v8, v60, v45
	v_fmac_f32_e32 v9, v60, v49
	s_cmpk_eq_i32 s24, 0x100
	s_cbranch_scc1 .Lwc_last
	v_add_co_u32_e32 v102, vcc, s27, v4
	global_load_dword v0, v[4:5], off
	s_nop 0
	v_addc_co_u32_e32 v103, vcc, 0, v5, vcc
	v_lshl_add_u64 v[106:107], v[6:7], 0, s[24:25]
	v_add_co_u32_e32 v104, vcc, s28, v4
	s_add_u32 s24, s24, 16
	s_nop 0
	v_addc_co_u32_e32 v105, vcc, 0, v5, vcc
	global_load_dwordx4 v[18:21], v[106:107], off
	global_load_dwordx4 v[22:25], v[106:107], off offset:256
	global_load_dwordx4 v[26:29], v[106:107], off offset:512
	global_load_dwordx4 v[30:33], v[106:107], off offset:768
	global_load_dwordx4 v[34:37], v[106:107], off offset:1024
	global_load_dwordx4 v[38:41], v[106:107], off offset:1280
	global_load_dwordx4 v[42:45], v[106:107], off offset:1536
	global_load_dwordx4 v[46:49], v[106:107], off offset:1792
	global_load_dword v56, v[102:103], off offset:-4096
	global_load_dword v58, v[102:103], off
	global_load_dword v60, v[104:105], off
	s_addc_u32 s25, s25, 0
	v_lshl_add_u64 v[4:5], v[4:5], 0, s[16:17]
	s_waitcnt vmcnt(12)
	v_fmac_f32_e32 v10, v62, v70
	v_fmac_f32_e32 v11, v62, v74
	v_fmac_f32_e32 v12, v62, v78
	v_fmac_f32_e32 v13, v62, v82
	v_fmac_f32_e32 v14, v62, v86
	v_fmac_f32_e32 v15, v62, v90
	v_fmac_f32_e32 v8, v62, v94
	v_fmac_f32_e32 v9, v62, v98
	v_fmac_f32_e32 v10, v64, v71
	v_fmac_f32_e32 v11, v64, v75
	v_fmac_f32_e32 v12, v64, v79
	v_fmac_f32_e32 v13, v64, v83
	v_fmac_f32_e32 v14, v64, v87
	v_fmac_f32_e32 v15, v64, v91
	v_fmac_f32_e32 v8, v64, v95
	v_fmac_f32_e32 v9, v64, v99
	v_fmac_f32_e32 v10, v66, v72
	v_fmac_f32_e32 v11, v66, v76
	v_fmac_f32_e32 v12, v66, v80
	v_fmac_f32_e32 v13, v66, v84
	v_fmac_f32_e32 v14, v66, v88
	v_fmac_f32_e32 v15, v66, v92
	v_fmac_f32_e32 v8, v66, v96
	v_fmac_f32_e32 v9, v66, v100
	v_fmac_f32_e32 v10, v68, v73
	v_fmac_f32_e32 v11, v68, v77
	v_fmac_f32_e32 v12, v68, v81
	v_fmac_f32_e32 v13, v68, v85
	v_fmac_f32_e32 v14, v68, v89
	v_fmac_f32_e32 v15, v68, v93
	v_fmac_f32_e32 v8, v68, v97
	v_fmac_f32_e32 v9, v68, v101
	s_branch .Lwc_loop
.Lwc_last:
	s_waitcnt vmcnt(0)
	v_fmac_f32_e32 v10, v62, v70
	v_fmac_f32_e32 v11, v62, v74
	v_fmac_f32_e32 v12, v62, v78
	v_fmac_f32_e32 v13, v62, v82
	v_fmac_f32_e32 v14, v62, v86
	v_fmac_f32_e32 v15, v62, v90
	v_fmac_f32_e32 v8, v62, v94
	v_fmac_f32_e32 v9, v62, v98
	v_fmac_f32_e32 v10, v64, v71
	v_fmac_f32_e32 v11, v64, v75
	v_fmac_f32_e32 v12, v64, v79
	v_fmac_f32_e32 v13, v64, v83
	v_fmac_f32_e32 v14, v64, v87
	v_fmac_f32_e32 v15, v64, v91
	v_fmac_f32_e32 v8, v64, v95
	v_fmac_f32_e32 v9, v64, v99
	v_fmac_f32_e32 v10, v66, v72
	v_fmac_f32_e32 v11, v66, v76
	v_fmac_f32_e32 v12, v66, v80
	v_fmac_f32_e32 v13, v66, v84
	v_fmac_f32_e32 v14, v66, v88
	v_fmac_f32_e32 v15, v66, v92
	v_fmac_f32_e32 v8, v66, v96
	v_fmac_f32_e32 v9, v66, v100
	v_fmac_f32_e32 v10, v68, v73
	v_fmac_f32_e32 v11, v68, v77
	v_fmac_f32_e32 v12, v68, v81
	v_fmac_f32_e32 v13, v68, v85
	v_fmac_f32_e32 v14, v68, v89
	v_fmac_f32_e32 v15, v68, v93
	v_fmac_f32_e32 v8, v68, v97
	v_fmac_f32_e32 v9, v68, v101
	v_and_b32_e32 v0, 0x3ff, v16
	v_lshlrev_b32_e32 v0, 12, v0
	v_lshlrev_b32_e32 v2, 7, v2
	v_cvt_pk_bf16_f32 v7, v8, v9
	v_lshl_add_u64 v[8:9], s[10:11], 0, v[0:1]
	v_ashrrev_i32_e32 v3, 31, v2
	v_lshrrev_b32_e32 v0, 6, v16
	v_add_u32_e32 v16, s3, v16
	v_lshl_add_u64 v[2:3], v[2:3], 1, v[8:9]
	v_and_b32_e32 v0, 0xf0, v0
	v_cmp_lt_i32_e32 vcc, s29, v16
	v_cvt_pk_bf16_f32 v4, v10, v11
	v_cvt_pk_bf16_f32 v5, v12, v13
	v_cvt_pk_bf16_f32 v6, v14, v15
	v_lshl_add_u64 v[2:3], v[2:3], 0, v[0:1]
	s_or_b64 s[14:15], vcc, s[14:15]
	v_subrev_u16_e32 v17, s3, v17
	global_store_dwordx4 v[2:3], v[4:7], off
	s_andn2_b64 exec, exec, s[14:15]
	s_cbranch_execnz .LBB0_122

.LBB0_1779:
	v_cmp_ge_u32_e64 s[90:91], v32, v66
	v_cmp_ge_u32_e64 s[92:93], v24, v66
	v_cmp_ge_u32_e64 s[94:95], v16, v66
	v_cmp_ge_u32_e32 vcc, v8, v66
	s_bcnt1_i32_b64 s6, s[90:91]
	s_add_i32 s6, s9, s6
	s_bcnt1_i32_b64 s7, s[92:93]
	s_add_i32 s6, s6, s7
	s_bcnt1_i32_b64 s7, s[94:95]
	s_add_i32 s6, s6, s7
	s_bcnt1_i32_b64 s7, vcc
	s_add_i32 s9, s6, s7

.LBB0_1781:
	v_lshlrev_b32_e64 v66, v65, 1
	s_mov_b32 s6, s8
	s_cmp_lt_i32 s6, 1
	v_or_b32_e32 v66, v66, v223
	s_cbranch_scc1 .LBB0_1783
	v_cmp_ge_u32_e64 s[90:91], v64, v66
	v_cmp_ge_u32_e64 s[92:93], v56, v66
	v_cmp_ge_u32_e64 s[94:95], v48, v66
	v_cmp_ge_u32_e32 vcc, v40, v66
	s_bcnt1_i32_b64 s7, s[90:91]
	s_bcnt1_i32_b64 s9, s[92:93]
	s_add_i32 s7, s9, s7
	s_bcnt1_i32_b64 s9, s[94:95]
	s_add_i32 s7, s7, s9
	s_bcnt1_i32_b64 s9, vcc
	s_add_i32 s9, s7, s9
	s_cmp_lt_i32 s6, 5
	s_cbranch_scc1 .LBB0_1780
	s_branch .LBB0_1779

.LBB0_1784:
	s_mov_b32 s6, s10
	s_cmp_lt_i32 s6, 1
	s_cbranch_scc1 .LBB0_1852
	v_cmp_ge_u32_e64 s[90:91], v64, v223
	v_cmp_ge_u32_e64 s[92:93], v63, v223
	v_cmp_ge_u32_e64 s[94:95], v62, v223
	v_cmp_ge_u32_e32 vcc, v61, v223
	s_bcnt1_i32_b64 s7, s[90:91]
	s_bcnt1_i32_b64 s8, s[92:93]
	s_add_i32 s7, s8, s7
	s_bcnt1_i32_b64 s8, s[94:95]
	s_add_i32 s7, s7, s8
	s_bcnt1_i32_b64 s8, vcc
	s_add_i32 s56, s7, s8
	s_cmp_lt_i32 s6, 5
	s_cbranch_scc1 .LBB0_1787
.LBB0_1786:
	v_cmp_ge_u32_e64 s[90:91], v60, v223
	v_cmp_ge_u32_e64 s[92:93], v59, v223
	v_cmp_ge_u32_e64 s[94:95], v58, v223
	v_cmp_ge_u32_e32 vcc, v57, v223
	s_bcnt1_i32_b64 s7, s[90:91]
	s_add_i32 s7, s56, s7
	s_bcnt1_i32_b64 s8, s[92:93]
	s_add_i32 s7, s7, s8
	s_bcnt1_i32_b64 s8, s[94:95]
	s_add_i32 s7, s7, s8
	s_bcnt1_i32_b64 s8, vcc
	s_add_i32 s56, s7, s8
.LBB0_1787:
	s_cmp_lt_i32 s6, 9
	s_cbranch_scc1 .LBB0_1801
	v_cmp_ge_u32_e64 s[90:91], v56, v223
	v_cmp_ge_u32_e64 s[92:93], v55, v223
	v_cmp_ge_u32_e64 s[94:95], v54, v223
	v_cmp_ge_u32_e32 vcc, v53, v223
	s_bcnt1_i32_b64 s7, s[90:91]
	s_add_i32 s7, s56, s7
	s_bcnt1_i32_b64 s8, s[92:93]
	s_add_i32 s7, s7, s8
	s_bcnt1_i32_b64 s8, s[94:95]
	s_add_i32 s7, s7, s8
	s_bcnt1_i32_b64 s8, vcc
	s_add_i32 s56, s7, s8
	s_cmp_lt_i32 s6, 13
	s_cbranch_scc0 .LBB0_1802

.LBB0_1790:
	v_cmp_ge_u32_e64 s[90:91], v48, v223
	v_cmp_ge_u32_e64 s[92:93], v47, v223
	v_cmp_ge_u32_e64 s[94:95], v46, v223
	v_cmp_ge_u32_e32 vcc, v45, v223
	s_bcnt1_i32_b64 s7, s[90:91]
	s_add_i32 s7, s56, s7
	s_bcnt1_i32_b64 s8, s[92:93]
	s_add_i32 s7, s7, s8
	s_bcnt1_i32_b64 s8, s[94:95]
	s_add_i32 s7, s7, s8
	s_bcnt1_i32_b64 s8, vcc
	s_add_i32 s56, s7, s8
	s_cmp_lt_i32 s6, 21
	s_cbranch_scc0 .LBB0_1804

.LBB0_1792:
	v_cmp_ge_u32_e64 s[90:91], v40, v223
	v_cmp_ge_u32_e64 s[92:93], v39, v223
	v_cmp_ge_u32_e64 s[94:95], v38, v223
	v_cmp_ge_u32_e32 vcc, v37, v223
	s_bcnt1_i32_b64 s7, s[90:91]
	s_add_i32 s7, s56, s7
	s_bcnt1_i32_b64 s8, s[92:93]
	s_add_i32 s7, s7, s8
	s_bcnt1_i32_b64 s8, s[94:95]
	s_add_i32 s7, s7, s8
	s_bcnt1_i32_b64 s8, vcc
	s_add_i32 s56, s7, s8
	s_cmp_lt_i32 s6, 29
	s_cbranch_scc0 .LBB0_1806

.LBB0_1794:
	v_cmp_ge_u32_e64 s[90:91], v32, v223
	v_cmp_ge_u32_e64 s[92:93], v31, v223
	v_cmp_ge_u32_e64 s[94:95], v30, v223
	v_cmp_ge_u32_e32 vcc, v29, v223
	s_bcnt1_i32_b64 s7, s[90:91]
	s_add_i32 s7, s56, s7
	s_bcnt1_i32_b64 s8, s[92:93]
	s_add_i32 s7, s7, s8
	s_bcnt1_i32_b64 s8, s[94:95]
	s_add_i32 s7, s7, s8
	s_bcnt1_i32_b64 s8, vcc
	s_add_i32 s56, s7, s8
	s_cmp_lt_i32 s6, 37
	s_cbranch_scc0 .LBB0_1808

.LBB0_1796:
	v_cmp_ge_u32_e64 s[90:91], v24, v223
	v_cmp_ge_u32_e64 s[92:93], v23, v223
	v_cmp_ge_u32_e64 s[94:95], v22, v223
	v_cmp_ge_u32_e32 vcc, v21, v223
	s_bcnt1_i32_b64 s7, s[90:91]
	s_add_i32 s7, s56, s7
	s_bcnt1_i32_b64 s8, s[92:93]
	s_add_i32 s7, s7, s8
	s_bcnt1_i32_b64 s8, s[94:95]
	s_add_i32 s7, s7, s8
	s_bcnt1_i32_b64 s8, vcc
	s_add_i32 s56, s7, s8
	s_cmp_lt_i32 s6, 45
	s_cbranch_scc0 .LBB0_1810

.LBB0_1798:
	v_cmp_ge_u32_e64 s[90:91], v16, v223
	v_cmp_ge_u32_e64 s[92:93], v15, v223
	v_cmp_ge_u32_e64 s[94:95], v14, v223
	v_cmp_ge_u32_e32 vcc, v13, v223
	s_bcnt1_i32_b64 s7, s[90:91]
	s_add_i32 s7, s56, s7
	s_bcnt1_i32_b64 s8, s[92:93]
	s_add_i32 s7, s7, s8
	s_bcnt1_i32_b64 s8, s[94:95]
	s_add_i32 s7, s7, s8
	s_bcnt1_i32_b64 s8, vcc
	s_add_i32 s56, s7, s8
	s_cmp_lt_i32 s6, 53
	s_cbranch_scc0 .LBB0_1812

.LBB0_1800:
	v_cmp_ge_u32_e64 s[90:91], v8, v223
	v_cmp_ge_u32_e64 s[92:93], v7, v223
	v_cmp_ge_u32_e64 s[94:95], v6, v223
	v_cmp_ge_u32_e32 vcc, v5, v223
	s_bcnt1_i32_b64 s7, s[90:91]
	s_add_i32 s7, s56, s7
	s_bcnt1_i32_b64 s8, s[92:93]
	s_add_i32 s7, s7, s8
	s_bcnt1_i32_b64 s8, s[94:95]
	s_add_i32 s7, s7, s8
	s_bcnt1_i32_b64 s8, vcc
	s_add_i32 s56, s7, s8
	s_cmp_lt_i32 s6, 61
	s_cbranch_scc0 .LBB0_1814
	s_branch .LBB0_1815

.LBB0_1802:
	v_cmp_ge_u32_e64 s[90:91], v52, v223
	v_cmp_ge_u32_e64 s[92:93], v51, v223
	v_cmp_ge_u32_e64 s[94:95], v50, v223
	v_cmp_ge_u32_e32 vcc, v49, v223
	s_bcnt1_i32_b64 s7, s[90:91]
	s_add_i32 s7, s56, s7
	s_bcnt1_i32_b64 s8, s[92:93]
	s_add_i32 s7, s7, s8
	s_bcnt1_i32_b64 s8, s[94:95]
	s_add_i32 s7, s7, s8
	s_bcnt1_i32_b64 s8, vcc
	s_add_i32 s56, s7, s8
	s_cmp_lt_i32 s6, 17
	s_cbranch_scc0 .LBB0_1790

.LBB0_1804:
	v_cmp_ge_u32_e64 s[90:91], v44, v223
	v_cmp_ge_u32_e64 s[92:93], v43, v223
	v_cmp_ge_u32_e64 s[94:95], v42, v223
	v_cmp_ge_u32_e32 vcc, v41, v223
	s_bcnt1_i32_b64 s7, s[90:91]
	s_add_i32 s7, s56, s7
	s_bcnt1_i32_b64 s8, s[92:93]
	s_add_i32 s7, s7, s8
	s_bcnt1_i32_b64 s8, s[94:95]
	s_add_i32 s7, s7, s8
	s_bcnt1_i32_b64 s8, vcc
	s_add_i32 s56, s7, s8
	s_cmp_lt_i32 s6, 25
	s_cbranch_scc0 .LBB0_1792

.LBB0_1806:
	v_cmp_ge_u32_e64 s[90:91], v36, v223
	v_cmp_ge_u32_e64 s[92:93], v35, v223
	v_cmp_ge_u32_e64 s[94:95], v34, v223
	v_cmp_ge_u32_e32 vcc, v33, v223
	s_bcnt1_i32_b64 s7, s[90:91]
	s_add_i32 s7, s56, s7
	s_bcnt1_i32_b64 s8, s[92:93]
	s_add_i32 s7, s7, s8
	s_bcnt1_i32_b64 s8, s[94:95]
	s_add_i32 s7, s7, s8
	s_bcnt1_i32_b64 s8, vcc
	s_add_i32 s56, s7, s8
	s_cmp_lt_i32 s6, 33
	s_cbranch_scc0 .LBB0_1794

.LBB0_1808:
	v_cmp_ge_u32_e64 s[90:91], v28, v223
	v_cmp_ge_u32_e64 s[92:93], v27, v223
	v_cmp_ge_u32_e64 s[94:95], v26, v223
	v_cmp_ge_u32_e32 vcc, v25, v223
	s_bcnt1_i32_b64 s7, s[90:91]
	s_add_i32 s7, s56, s7
	s_bcnt1_i32_b64 s8, s[92:93]
	s_add_i32 s7, s7, s8
	s_bcnt1_i32_b64 s8, s[94:95]
	s_add_i32 s7, s7, s8
	s_bcnt1_i32_b64 s8, vcc
	s_add_i32 s56, s7, s8
	s_cmp_lt_i32 s6, 41
	s_cbranch_scc0 .LBB0_1796

.LBB0_1810:
	v_cmp_ge_u32_e64 s[90:91], v20, v223
	v_cmp_ge_u32_e64 s[92:93], v19, v223
	v_cmp_ge_u32_e64 s[94:95], v18, v223
	v_cmp_ge_u32_e32 vcc, v17, v223
	s_bcnt1_i32_b64 s7, s[90:91]
	s_add_i32 s7, s56, s7
	s_bcnt1_i32_b64 s8, s[92:93]
	s_add_i32 s7, s7, s8
	s_bcnt1_i32_b64 s8, s[94:95]
	s_add_i32 s7, s7, s8
	s_bcnt1_i32_b64 s8, vcc
	s_add_i32 s56, s7, s8
	s_cmp_lt_i32 s6, 49
	s_cbranch_scc0 .LBB0_1798

.LBB0_1812:
	v_cmp_ge_u32_e64 s[90:91], v12, v223
	v_cmp_ge_u32_e64 s[92:93], v11, v223
	v_cmp_ge_u32_e64 s[94:95], v10, v223
	v_cmp_ge_u32_e32 vcc, v9, v223
	s_bcnt1_i32_b64 s7, s[90:91]
	s_add_i32 s7, s56, s7
	s_bcnt1_i32_b64 s8, s[92:93]
	s_add_i32 s7, s7, s8
	s_bcnt1_i32_b64 s8, s[94:95]
	s_add_i32 s7, s7, s8
	s_bcnt1_i32_b64 s8, vcc
	s_add_i32 s56, s7, s8
	s_cmp_lt_i32 s6, 57
	s_cbranch_scc0 .LBB0_1800

.LBB0_1814:
	v_cmp_ge_u32_e64 s[90:91], v4, v223
	v_cmp_ge_u32_e64 s[92:93], v3, v223
	v_cmp_ge_u32_e64 s[94:95], v2, v223
	v_cmp_ge_u32_e32 vcc, v0, v223
	s_bcnt1_i32_b64 s6, s[90:91]
	s_add_i32 s6, s56, s6
	s_bcnt1_i32_b64 s7, s[92:93]
	s_add_i32 s6, s6, s7
	s_bcnt1_i32_b64 s7, s[94:95]
	s_add_i32 s6, s6, s7
	s_bcnt1_i32_b64 s7, vcc
	s_add_i32 s56, s6, s7

.LBB0_1818:
	v_lshlrev_b32_e64 v67, v66, 1
	s_mov_b32 s6, s10
	s_cmp_lt_i32 s6, 1
	v_or_b32_e32 v67, v67, v65
	s_cbranch_scc1 .LBB0_1849
	v_cmp_ge_u32_e64 s[90:91], v64, v67
	v_cmp_ge_u32_e64 s[92:93], v63, v67
	v_cmp_ge_u32_e64 s[94:95], v62, v67
	v_cmp_ge_u32_e32 vcc, v61, v67
	s_bcnt1_i32_b64 s7, s[90:91]
	s_bcnt1_i32_b64 s8, s[92:93]
	s_add_i32 s7, s8, s7
	s_bcnt1_i32_b64 s8, s[94:95]
	s_add_i32 s7, s7, s8
	s_bcnt1_i32_b64 s8, vcc
	s_add_i32 s8, s7, s8
	s_cmp_lt_i32 s6, 5
	s_cbranch_scc1 .LBB0_1821
.LBB0_1820:
	v_cmp_ge_u32_e64 s[90:91], v60, v67
	v_cmp_ge_u32_e64 s[92:93], v59, v67
	v_cmp_ge_u32_e64 s[94:95], v58, v67
	v_cmp_ge_u32_e32 vcc, v57, v67
	s_bcnt1_i32_b64 s7, s[90:91]
	s_add_i32 s7, s8, s7
	s_bcnt1_i32_b64 s8, s[92:93]
	s_add_i32 s7, s7, s8
	s_bcnt1_i32_b64 s8, s[94:95]
	s_add_i32 s7, s7, s8
	s_bcnt1_i32_b64 s8, vcc
	s_add_i32 s8, s7, s8
.LBB0_1821:
	s_cmp_lt_i32 s6, 9
	s_cbranch_scc1 .LBB0_1835
	v_cmp_ge_u32_e64 s[90:91], v56, v67
	v_cmp_ge_u32_e64 s[92:93], v55, v67
	v_cmp_ge_u32_e64 s[94:95], v54, v67
	v_cmp_ge_u32_e32 vcc, v53, v67
	s_bcnt1_i32_b64 s7, s[90:91]
	s_add_i32 s7, s8, s7
	s_bcnt1_i32_b64 s8, s[92:93]
	s_add_i32 s7, s7, s8
	s_bcnt1_i32_b64 s8, s[94:95]
	s_add_i32 s7, s7, s8
	s_bcnt1_i32_b64 s8, vcc
	s_add_i32 s8, s7, s8
	s_cmp_lt_i32 s6, 13
	s_cbranch_scc0 .LBB0_1836

.LBB0_1824:
	v_cmp_ge_u32_e64 s[90:91], v48, v67
	v_cmp_ge_u32_e64 s[92:93], v47, v67
	v_cmp_ge_u32_e64 s[94:95], v46, v67
	v_cmp_ge_u32_e32 vcc, v45, v67
	s_bcnt1_i32_b64 s7, s[90:91]
	s_add_i32 s7, s8, s7
	s_bcnt1_i32_b64 s8, s[92:93]
	s_add_i32 s7, s7, s8
	s_bcnt1_i32_b64 s8, s[94:95]
	s_add_i32 s7, s7, s8
	s_bcnt1_i32_b64 s8, vcc
	s_add_i32 s8, s7, s8
	s_cmp_lt_i32 s6, 21
	s_cbranch_scc0 .LBB0_1838

.LBB0_1826:
	v_cmp_ge_u32_e64 s[90:91], v40, v67
	v_cmp_ge_u32_e64 s[92:93], v39, v67
	v_cmp_ge_u32_e64 s[94:95], v38, v67
	v_cmp_ge_u32_e32 vcc, v37, v67
	s_bcnt1_i32_b64 s7, s[90:91]
	s_add_i32 s7, s8, s7
	s_bcnt1_i32_b64 s8, s[92:93]
	s_add_i32 s7, s7, s8
	s_bcnt1_i32_b64 s8, s[94:95]
	s_add_i32 s7, s7, s8
	s_bcnt1_i32_b64 s8, vcc
	s_add_i32 s8, s7, s8
	s_cmp_lt_i32 s6, 29
	s_cbranch_scc0 .LBB0_1840

.LBB0_1828:
	v_cmp_ge_u32_e64 s[90:91], v32, v67
	v_cmp_ge_u32_e64 s[92:93], v31, v67
	v_cmp_ge_u32_e64 s[94:95], v30, v67
	v_cmp_ge_u32_e32 vcc, v29, v67
	s_bcnt1_i32_b64 s7, s[90:91]
	s_add_i32 s7, s8, s7
	s_bcnt1_i32_b64 s8, s[92:93]
	s_add_i32 s7, s7, s8
	s_bcnt1_i32_b64 s8, s[94:95]
	s_add_i32 s7, s7, s8
	s_bcnt1_i32_b64 s8, vcc
	s_add_i32 s8, s7, s8
	s_cmp_lt_i32 s6, 37
	s_cbranch_scc0 .LBB0_1842

.LBB0_1830:
	v_cmp_ge_u32_e64 s[90:91], v24, v67
	v_cmp_ge_u32_e64 s[92:93], v23, v67
	v_cmp_ge_u32_e64 s[94:95], v22, v67
	v_cmp_ge_u32_e32 vcc, v21, v67
	s_bcnt1_i32_b64 s7, s[90:91]
	s_add_i32 s7, s8, s7
	s_bcnt1_i32_b64 s8, s[92:93]
	s_add_i32 s7, s7, s8
	s_bcnt1_i32_b64 s8, s[94:95]
	s_add_i32 s7, s7, s8
	s_bcnt1_i32_b64 s8, vcc
	s_add_i32 s8, s7, s8
	s_cmp_lt_i32 s6, 45
	s_cbranch_scc0 .LBB0_1844

.LBB0_1832:
	v_cmp_ge_u32_e64 s[90:91], v16, v67
	v_cmp_ge_u32_e64 s[92:93], v15, v67
	v_cmp_ge_u32_e64 s[94:95], v14, v67
	v_cmp_ge_u32_e32 vcc, v13, v67
	s_bcnt1_i32_b64 s7, s[90:91]
	s_add_i32 s7, s8, s7
	s_bcnt1_i32_b64 s8, s[92:93]
	s_add_i32 s7, s7, s8
	s_bcnt1_i32_b64 s8, s[94:95]
	s_add_i32 s7, s7, s8
	s_bcnt1_i32_b64 s8, vcc
	s_add_i32 s8, s7, s8
	s_cmp_lt_i32 s6, 53
	s_cbranch_scc0 .LBB0_1846

.LBB0_1834:
	v_cmp_ge_u32_e64 s[90:91], v8, v67
	v_cmp_ge_u32_e64 s[92:93], v7, v67
	v_cmp_ge_u32_e64 s[94:95], v6, v67
	v_cmp_ge_u32_e32 vcc, v5, v67
	s_bcnt1_i32_b64 s7, s[90:91]
	s_add_i32 s7, s8, s7
	s_bcnt1_i32_b64 s8, s[92:93]
	s_add_i32 s7, s7, s8
	s_bcnt1_i32_b64 s8, s[94:95]
	s_add_i32 s7, s7, s8
	s_bcnt1_i32_b64 s8, vcc
	s_add_i32 s8, s7, s8
	s_cmp_lt_i32 s6, 61
	s_cbranch_scc1 .LBB0_1817
	s_branch .LBB0_1848

.LBB0_1836:
	v_cmp_ge_u32_e64 s[90:91], v52, v67
	v_cmp_ge_u32_e64 s[92:93], v51, v67
	v_cmp_ge_u32_e64 s[94:95], v50, v67
	v_cmp_ge_u32_e32 vcc, v49, v67
	s_bcnt1_i32_b64 s7, s[90:91]
	s_add_i32 s7, s8, s7
	s_bcnt1_i32_b64 s8, s[92:93]
	s_add_i32 s7, s7, s8
	s_bcnt1_i32_b64 s8, s[94:95]
	s_add_i32 s7, s7, s8
	s_bcnt1_i32_b64 s8, vcc
	s_add_i32 s8, s7, s8
	s_cmp_lt_i32 s6, 17
	s_cbranch_scc0 .LBB0_1824

.LBB0_1838:
	v_cmp_ge_u32_e64 s[90:91], v44, v67
	v_cmp_ge_u32_e64 s[92:93], v43, v67
	v_cmp_ge_u32_e64 s[94:95], v42, v67
	v_cmp_ge_u32_e32 vcc, v41, v67
	s_bcnt1_i32_b64 s7, s[90:91]
	s_add_i32 s7, s8, s7
	s_bcnt1_i32_b64 s8, s[92:93]
	s_add_i32 s7, s7, s8
	s_bcnt1_i32_b64 s8, s[94:95]
	s_add_i32 s7, s7, s8
	s_bcnt1_i32_b64 s8, vcc
	s_add_i32 s8, s7, s8
	s_cmp_lt_i32 s6, 25
	s_cbranch_scc0 .LBB0_1826

.LBB0_1840:
	v_cmp_ge_u32_e64 s[90:91], v36, v67
	v_cmp_ge_u32_e64 s[92:93], v35, v67
	v_cmp_ge_u32_e64 s[94:95], v34, v67
	v_cmp_ge_u32_e32 vcc, v33, v67
	s_bcnt1_i32_b64 s7, s[90:91]
	s_add_i32 s7, s8, s7
	s_bcnt1_i32_b64 s8, s[92:93]
	s_add_i32 s7, s7, s8
	s_bcnt1_i32_b64 s8, s[94:95]
	s_add_i32 s7, s7, s8
	s_bcnt1_i32_b64 s8, vcc
	s_add_i32 s8, s7, s8
	s_cmp_lt_i32 s6, 33
	s_cbranch_scc0 .LBB0_1828

.LBB0_1842:
	v_cmp_ge_u32_e64 s[90:91], v28, v67
	v_cmp_ge_u32_e64 s[92:93], v27, v67
	v_cmp_ge_u32_e64 s[94:95], v26, v67
	v_cmp_ge_u32_e32 vcc, v25, v67
	s_bcnt1_i32_b64 s7, s[90:91]
	s_add_i32 s7, s8, s7
	s_bcnt1_i32_b64 s8, s[92:93]
	s_add_i32 s7, s7, s8
	s_bcnt1_i32_b64 s8, s[94:95]
	s_add_i32 s7, s7, s8
	s_bcnt1_i32_b64 s8, vcc
	s_add_i32 s8, s7, s8
	s_cmp_lt_i32 s6, 41
	s_cbranch_scc0 .LBB0_1830

.LBB0_1844:
	v_cmp_ge_u32_e64 s[90:91], v20, v67
	v_cmp_ge_u32_e64 s[92:93], v19, v67
	v_cmp_ge_u32_e64 s[94:95], v18, v67
	v_cmp_ge_u32_e32 vcc, v17, v67
	s_bcnt1_i32_b64 s7, s[90:91]
	s_add_i32 s7, s8, s7
	s_bcnt1_i32_b64 s8, s[92:93]
	s_add_i32 s7, s7, s8
	s_bcnt1_i32_b64 s8, s[94:95]
	s_add_i32 s7, s7, s8
	s_bcnt1_i32_b64 s8, vcc
	s_add_i32 s8, s7, s8
	s_cmp_lt_i32 s6, 49
	s_cbranch_scc0 .LBB0_1832

.LBB0_1846:
	v_cmp_ge_u32_e64 s[90:91], v12, v67
	v_cmp_ge_u32_e64 s[92:93], v11, v67
	v_cmp_ge_u32_e64 s[94:95], v10, v67
	v_cmp_ge_u32_e32 vcc, v9, v67
	s_bcnt1_i32_b64 s7, s[90:91]
	s_add_i32 s7, s8, s7
	s_bcnt1_i32_b64 s8, s[92:93]
	s_add_i32 s7, s7, s8
	s_bcnt1_i32_b64 s8, s[94:95]
	s_add_i32 s7, s7, s8
	s_bcnt1_i32_b64 s8, vcc
	s_add_i32 s8, s7, s8
	s_cmp_lt_i32 s6, 57
	s_cbranch_scc0 .LBB0_1834

.LBB0_1848:
	v_cmp_ge_u32_e64 s[90:91], v4, v67
	v_cmp_ge_u32_e64 s[92:93], v3, v67
	v_cmp_ge_u32_e64 s[94:95], v2, v67
	v_cmp_ge_u32_e32 vcc, v0, v67
	s_bcnt1_i32_b64 s6, s[90:91]
	s_add_i32 s6, s8, s6
	s_bcnt1_i32_b64 s7, s[92:93]
	s_add_i32 s6, s6, s7
	s_bcnt1_i32_b64 s7, s[94:95]
	s_add_i32 s6, s6, s7
	s_bcnt1_i32_b64 s7, vcc
	s_add_i32 s8, s6, s7
	s_branch .LBB0_1817

.LBB0_2426:
	v_lshlrev_b32_e64 v19, v18, 1
	s_mov_b32 s12, s57
	s_cmp_lt_i32 s12, 1
	v_or_b32_e32 v19, v19, v0
	s_cbranch_scc1 .LBB0_2433
	v_cmp_ge_u32_e64 s[90:91], v17, v19
	v_cmp_ge_u32_e64 s[92:93], v3, v19
	v_cmp_ge_u32_e64 s[94:95], v2, v19
	v_cmp_ge_u32_e32 vcc, v16, v19
	s_bcnt1_i32_b64 s13, s[90:91]
	s_bcnt1_i32_b64 s40, s[92:93]
	s_add_i32 s13, s40, s13
	s_bcnt1_i32_b64 s40, s[94:95]
	s_add_i32 s13, s13, s40
	s_bcnt1_i32_b64 s40, vcc
	s_add_i32 s40, s13, s40
	s_cmp_lt_i32 s12, 5
	s_cbranch_scc1 .LBB0_2429
.LBB0_2428:
	v_cmp_ge_u32_e64 s[90:91], v15, v19
	v_cmp_ge_u32_e64 s[92:93], v14, v19
	v_cmp_ge_u32_e64 s[94:95], v13, v19
	v_cmp_ge_u32_e32 vcc, v12, v19
	s_bcnt1_i32_b64 s13, s[90:91]
	s_add_i32 s13, s40, s13
	s_bcnt1_i32_b64 s40, s[92:93]
	s_add_i32 s13, s13, s40
	s_bcnt1_i32_b64 s40, s[94:95]
	s_add_i32 s13, s13, s40
	s_bcnt1_i32_b64 s40, vcc
	s_add_i32 s40, s13, s40
.LBB0_2429:
	s_cmp_lt_i32 s12, 9
	s_cbranch_scc1 .LBB0_2431
	v_cmp_ge_u32_e64 s[90:91], v11, v19
	v_cmp_ge_u32_e64 s[92:93], v10, v19
	v_cmp_ge_u32_e64 s[94:95], v9, v19
	v_cmp_ge_u32_e32 vcc, v8, v19
	s_bcnt1_i32_b64 s13, s[90:91]
	s_add_i32 s13, s40, s13
	s_bcnt1_i32_b64 s40, s[92:93]
	s_add_i32 s13, s13, s40
	s_bcnt1_i32_b64 s40, s[94:95]
	s_add_i32 s13, s13, s40
	s_bcnt1_i32_b64 s40, vcc
	s_add_i32 s40, s13, s40
	s_cmp_lt_i32 s12, 13
	s_cbranch_scc1 .LBB0_2425
	s_branch .LBB0_2432

.LBB0_2432:
	v_cmp_ge_u32_e64 s[90:91], v7, v19
	v_cmp_ge_u32_e64 s[92:93], v6, v19
	v_cmp_ge_u32_e64 s[94:95], v5, v19
	v_cmp_ge_u32_e32 vcc, v4, v19
	s_bcnt1_i32_b64 s12, s[90:91]
	s_add_i32 s12, s40, s12
	s_bcnt1_i32_b64 s13, s[92:93]
	s_add_i32 s12, s12, s13
	s_bcnt1_i32_b64 s13, s[94:95]
	s_add_i32 s12, s12, s13
	s_bcnt1_i32_b64 s13, vcc
	s_add_i32 s40, s12, s13
	s_branch .LBB0_2425
